# dma+cvt2+sc1(P1 stores) + nt streaming policy on P3 gate loads and P4 residual loads
# speedup vs baseline: 1.0141x; 1.0141x over previous
.LBB0_499:
	s_lshl_b32 s0, s49, 8
	v_readlane_b32 s1, v254, 61
	v_mbcnt_lo_u32_b32 v130, -1, 0
	v_mbcnt_hi_u32_b32 v130, -1, v130
	s_add_i32 s0, s0, s1
	v_and_or_b32 v156, v130, 15, s0
	s_lshl_b32 s0, s48, 8
	v_ashrrev_i32_e32 v130, 1, v130
	v_and_b32_e32 v130, -8, v130
	s_or_b32 s0, s0, s81
	v_add_u32_e32 v154, s0, v130
	v_mov_b64_e32 v[130:131], s[10:11]
	v_mad_i64_i32 v[130:131], s[0:1], v156, s87, v[130:131]
	s_lshl_b32 s0, s47, 11
	s_ashr_i32 s1, s0, 31
	v_lshl_add_u64 v[130:131], s[0:1], 1, v[130:131]
	v_ashrrev_i32_e32 v155, 31, v154
	v_lshl_add_u64 v[134:135], v[154:155], 1, v[130:131]
	v_add_co_u32_e32 v130, vcc, 0x5000, v134
	s_cmp_gt_i32 s47, 2
	s_nop 0
	v_addc_co_u32_e32 v131, vcc, 0, v135, vcc
	global_load_dwordx4 v[130:133], v[130:131], off nt
	s_cselect_b64 s[26:27], -1, 0
	s_mov_b64 s[4:5], 0x5000
	s_mov_b64 s[0:1], -1
	s_and_b64 vcc, exec, s[26:27]
	v_lshl_add_u64 v[214:215], v[134:135], 0, s[4:5]
	s_waitcnt vmcnt(0)
	v_lshlrev_b32_e32 v192, 16, v130
	v_and_b32_e32 v193, 0xffff0000, v130
	v_lshlrev_b32_e32 v190, 16, v131
	v_and_b32_e32 v191, 0xffff0000, v131
	v_lshlrev_b32_e32 v188, 16, v132
	v_and_b32_e32 v189, 0xffff0000, v132
	v_lshlrev_b32_e32 v186, 16, v133
	v_and_b32_e32 v187, 0xffff0000, v133
	s_cbranch_vccnz .LBB0_502
	s_andn2_b64 vcc, exec, s[0:1]
	s_cbranch_vccz .LBB0_503

.LBB0_502:
	global_load_dwordx4 v[160:163], v[214:215], off offset:256 nt
	v_add_co_u32_e32 v130, vcc, 0x90000, v214
	v_ashrrev_i32_e32 v157, 31, v156
	s_nop 0
	v_addc_co_u32_e32 v131, vcc, 0, v215, vcc
	global_load_dwordx4 v[150:153], v[130:131], off nt
	global_load_dwordx4 v[146:149], v[130:131], off offset:256 nt
	v_add_co_u32_e32 v130, vcc, 0x120000, v214
	v_pk_mul_f32 v[164:165], v[126:127], v[192:193]
	s_nop 0
	v_addc_co_u32_e32 v131, vcc, 0, v215, vcc
	global_load_dwordx4 v[142:145], v[130:131], off nt
	global_load_dwordx4 v[138:141], v[130:131], off offset:256 nt
	v_add_co_u32_e32 v130, vcc, 0x1b0000, v214
	v_pk_mul_f32 v[166:167], v[128:129], v[190:191]
	s_nop 0
	v_addc_co_u32_e32 v131, vcc, 0, v215, vcc
	global_load_dwordx4 v[134:137], v[130:131], off nt
	s_nop 0
	global_load_dwordx4 v[130:133], v[130:131], off offset:256 nt
	v_lshlrev_b64 v[158:159], 12, v[156:157]
	v_cvt_pk_bf16_f32 v164, v164, v165
	v_cvt_pk_bf16_f32 v165, v166, v167
	v_pk_mul_f32 v[166:167], v[122:123], v[188:189]
	v_pk_mul_f32 v[168:169], v[124:125], v[186:187]
	v_cvt_pk_bf16_f32 v166, v166, v167
	v_cvt_pk_bf16_f32 v167, v168, v169
	v_lshl_add_u64 v[168:169], s[12:13], 0, v[158:159]
	v_lshlrev_b64 v[158:159], 1, v[154:155]
	v_lshl_add_u64 v[154:155], v[168:169], 0, v[158:159]
	global_store_dwordx4 v[154:155], v[164:167], off
	s_mov_b32 s0, 0x480000
	s_waitcnt vmcnt(7)
	v_lshlrev_b32_e32 v164, 16, v160
	v_and_b32_e32 v165, 0xffff0000, v160
	v_pk_mul_f32 v[164:165], v[94:95], v[164:165]
	s_nop 0
	v_cvt_pk_bf16_f32 v160, v164, v165
	v_lshlrev_b32_e32 v164, 16, v161
	v_and_b32_e32 v165, 0xffff0000, v161
	v_pk_mul_f32 v[164:165], v[96:97], v[164:165]
	s_nop 0
	v_cvt_pk_bf16_f32 v161, v164, v165
	v_lshlrev_b32_e32 v164, 16, v162
	v_and_b32_e32 v165, 0xffff0000, v162
	v_pk_mul_f32 v[164:165], v[90:91], v[164:165]
	s_nop 0
	v_cvt_pk_bf16_f32 v162, v164, v165
	v_lshlrev_b32_e32 v164, 16, v163
	v_and_b32_e32 v165, 0xffff0000, v163
	v_pk_mul_f32 v[164:165], v[92:93], v[164:165]
	s_nop 0
	v_cvt_pk_bf16_f32 v163, v164, v165
	global_store_dwordx4 v[154:155], v[160:163], off offset:256
	s_waitcnt vmcnt(7)
	s_nop 0
	v_lshlrev_b32_e32 v162, 16, v150
	v_and_b32_e32 v163, 0xffff0000, v150
	v_pk_mul_f32 v[162:163], v[118:119], v[162:163]
	v_or_b32_e32 v160, 16, v156
	v_cvt_pk_bf16_f32 v150, v162, v163
	v_lshlrev_b32_e32 v162, 16, v151
	v_and_b32_e32 v163, 0xffff0000, v151
	v_pk_mul_f32 v[162:163], v[120:121], v[162:163]
	v_ashrrev_i32_e32 v161, 31, v160
	v_cvt_pk_bf16_f32 v151, v162, v163
	v_lshlrev_b32_e32 v162, 16, v152
	v_and_b32_e32 v163, 0xffff0000, v152
	v_pk_mul_f32 v[162:163], v[114:115], v[162:163]
	v_lshlrev_b64 v[160:161], 12, v[160:161]
	v_cvt_pk_bf16_f32 v152, v162, v163
	v_lshlrev_b32_e32 v162, 16, v153
	v_and_b32_e32 v163, 0xffff0000, v153
	v_pk_mul_f32 v[162:163], v[116:117], v[162:163]
	v_lshl_add_u64 v[160:161], s[12:13], 0, v[160:161]
	v_cvt_pk_bf16_f32 v153, v162, v163
	v_lshl_add_u64 v[160:161], v[160:161], 0, v[158:159]
	global_store_dwordx4 v[160:161], v[150:153], off
	s_waitcnt vmcnt(7)
	s_nop 0
	v_lshlrev_b32_e32 v150, 16, v146
	v_and_b32_e32 v151, 0xffff0000, v146
	v_pk_mul_f32 v[150:151], v[86:87], v[150:151]
	s_nop 0
	v_cvt_pk_bf16_f32 v146, v150, v151
	v_lshlrev_b32_e32 v150, 16, v147
	v_and_b32_e32 v151, 0xffff0000, v147
	v_pk_mul_f32 v[150:151], v[88:89], v[150:151]
	s_nop 0
	v_cvt_pk_bf16_f32 v147, v150, v151
	v_lshlrev_b32_e32 v150, 16, v148
	v_and_b32_e32 v151, 0xffff0000, v148
	v_pk_mul_f32 v[150:151], v[82:83], v[150:151]
	s_nop 0
	v_cvt_pk_bf16_f32 v148, v150, v151
	v_lshlrev_b32_e32 v150, 16, v149
	v_and_b32_e32 v151, 0xffff0000, v149
	v_pk_mul_f32 v[150:151], v[84:85], v[150:151]
	s_nop 0
	v_cvt_pk_bf16_f32 v149, v150, v151
	global_store_dwordx4 v[160:161], v[146:149], off offset:256
	s_waitcnt vmcnt(7)
	s_nop 0
	v_lshlrev_b32_e32 v148, 16, v142
	v_and_b32_e32 v149, 0xffff0000, v142
	v_pk_mul_f32 v[148:149], v[110:111], v[148:149]
	v_or_b32_e32 v146, 32, v156
	v_cvt_pk_bf16_f32 v142, v148, v149
	v_lshlrev_b32_e32 v148, 16, v143
	v_and_b32_e32 v149, 0xffff0000, v143
	v_pk_mul_f32 v[148:149], v[112:113], v[148:149]
	v_ashrrev_i32_e32 v147, 31, v146
	v_cvt_pk_bf16_f32 v143, v148, v149
	v_lshlrev_b32_e32 v148, 16, v144
	v_and_b32_e32 v149, 0xffff0000, v144
	v_pk_mul_f32 v[148:149], v[106:107], v[148:149]
	v_lshlrev_b64 v[146:147], 12, v[146:147]
	v_cvt_pk_bf16_f32 v144, v148, v149
	v_lshlrev_b32_e32 v148, 16, v145
	v_and_b32_e32 v149, 0xffff0000, v145
	v_pk_mul_f32 v[148:149], v[108:109], v[148:149]
	v_lshl_add_u64 v[146:147], s[12:13], 0, v[146:147]
	v_cvt_pk_bf16_f32 v145, v148, v149
	v_lshl_add_u64 v[146:147], v[146:147], 0, v[158:159]
	global_store_dwordx4 v[146:147], v[142:145], off
	s_waitcnt vmcnt(7)
	s_nop 0
	v_lshlrev_b32_e32 v142, 16, v138
	v_and_b32_e32 v143, 0xffff0000, v138
	v_pk_mul_f32 v[142:143], v[78:79], v[142:143]
	s_nop 0
	v_cvt_pk_bf16_f32 v138, v142, v143
	v_lshlrev_b32_e32 v142, 16, v139
	v_and_b32_e32 v143, 0xffff0000, v139
	v_pk_mul_f32 v[142:143], v[80:81], v[142:143]
	s_nop 0
	v_cvt_pk_bf16_f32 v139, v142, v143
	v_lshlrev_b32_e32 v142, 16, v140
	v_and_b32_e32 v143, 0xffff0000, v140
	v_pk_mul_f32 v[142:143], v[74:75], v[142:143]
	s_nop 0
	v_cvt_pk_bf16_f32 v140, v142, v143
	v_lshlrev_b32_e32 v142, 16, v141
	v_and_b32_e32 v143, 0xffff0000, v141
	v_pk_mul_f32 v[142:143], v[76:77], v[142:143]
	s_nop 0
	v_cvt_pk_bf16_f32 v141, v142, v143
	global_store_dwordx4 v[146:147], v[138:141], off offset:256
	s_waitcnt vmcnt(7)
	s_nop 0
	v_lshlrev_b32_e32 v140, 16, v134
	v_and_b32_e32 v141, 0xffff0000, v134
	v_pk_mul_f32 v[140:141], v[102:103], v[140:141]
	v_or_b32_e32 v138, 48, v156
	v_cvt_pk_bf16_f32 v134, v140, v141
	v_lshlrev_b32_e32 v140, 16, v135
	v_and_b32_e32 v141, 0xffff0000, v135
	v_pk_mul_f32 v[140:141], v[104:105], v[140:141]
	v_ashrrev_i32_e32 v139, 31, v138
	v_cvt_pk_bf16_f32 v135, v140, v141
	v_lshlrev_b32_e32 v140, 16, v136
	v_and_b32_e32 v141, 0xffff0000, v136
	v_pk_mul_f32 v[140:141], v[98:99], v[140:141]
	v_lshlrev_b64 v[138:139], 12, v[138:139]
	v_cvt_pk_bf16_f32 v136, v140, v141
	v_lshlrev_b32_e32 v140, 16, v137
	v_and_b32_e32 v141, 0xffff0000, v137
	v_pk_mul_f32 v[140:141], v[100:101], v[140:141]
	v_lshl_add_u64 v[138:139], s[12:13], 0, v[138:139]
	v_cvt_pk_bf16_f32 v137, v140, v141
	v_lshl_add_u64 v[138:139], v[138:139], 0, v[158:159]
	global_store_dwordx4 v[138:139], v[134:137], off
	s_waitcnt vmcnt(7)
	s_nop 0
	v_lshlrev_b32_e32 v134, 16, v130
	v_and_b32_e32 v135, 0xffff0000, v130
	v_pk_mul_f32 v[134:135], v[70:71], v[134:135]
	s_nop 0
	v_cvt_pk_bf16_f32 v130, v134, v135
	v_lshlrev_b32_e32 v134, 16, v131
	v_and_b32_e32 v135, 0xffff0000, v131
	v_pk_mul_f32 v[134:135], v[72:73], v[134:135]
	s_nop 0
	v_cvt_pk_bf16_f32 v131, v134, v135
	v_lshlrev_b32_e32 v134, 16, v132
	v_and_b32_e32 v135, 0xffff0000, v132
	v_pk_mul_f32 v[134:135], v[66:67], v[134:135]
	s_nop 0
	v_cvt_pk_bf16_f32 v132, v134, v135
	v_lshlrev_b32_e32 v134, 16, v133
	v_and_b32_e32 v135, 0xffff0000, v133
	v_pk_mul_f32 v[134:135], v[68:69], v[134:135]
	s_nop 0
	v_cvt_pk_bf16_f32 v133, v134, v135
	global_store_dwordx4 v[138:139], v[130:133], off offset:256
	s_nop 1
	v_add_co_u32_e32 v130, vcc, s0, v214
	s_mov_b32 s0, 0x510000
	s_nop 0
	v_addc_co_u32_e32 v131, vcc, 0, v215, vcc
	global_load_dwordx4 v[134:137], v[130:131], off nt
	global_load_dwordx4 v[138:141], v[130:131], off offset:256 nt
	v_add_co_u32_e32 v130, vcc, s0, v214
	s_mov_b32 s0, 0x5a0000
	s_nop 0
	v_addc_co_u32_e32 v131, vcc, 0, v215, vcc
	global_load_dwordx4 v[142:145], v[130:131], off nt
	global_load_dwordx4 v[146:149], v[130:131], off offset:256 nt
	v_add_co_u32_e32 v130, vcc, s0, v214
	s_mov_b32 s0, 0x630000
	s_nop 0
	v_addc_co_u32_e32 v131, vcc, 0, v215, vcc
	global_load_dwordx4 v[150:153], v[130:131], off nt
	global_load_dwordx4 v[156:159], v[130:131], off offset:256 nt
	v_add_co_u32_e32 v130, vcc, s0, v214
	s_mov_b64 s[0:1], 0x80000
	s_nop 0
	v_addc_co_u32_e32 v131, vcc, 0, v215, vcc
	global_load_dwordx4 v[160:163], v[130:131], off nt
	s_nop 0
	global_load_dwordx4 v[130:133], v[130:131], off offset:256 nt
	s_waitcnt vmcnt(7)
	v_lshlrev_b32_e32 v164, 16, v134
	v_and_b32_e32 v165, 0xffff0000, v134
	v_pk_mul_f32 v[164:165], v[62:63], v[164:165]
	s_nop 0
	v_cvt_pk_bf16_f32 v134, v164, v165
	v_lshlrev_b32_e32 v164, 16, v135
	v_and_b32_e32 v165, 0xffff0000, v135
	v_pk_mul_f32 v[164:165], v[64:65], v[164:165]
	s_nop 0
	v_cvt_pk_bf16_f32 v135, v164, v165
	v_lshlrev_b32_e32 v164, 16, v136
	v_and_b32_e32 v165, 0xffff0000, v136
	v_pk_mul_f32 v[164:165], v[58:59], v[164:165]
	s_nop 0
	v_cvt_pk_bf16_f32 v136, v164, v165
	v_lshlrev_b32_e32 v164, 16, v137
	v_and_b32_e32 v165, 0xffff0000, v137
	v_pk_mul_f32 v[164:165], v[60:61], v[164:165]
	s_nop 0
	v_cvt_pk_bf16_f32 v137, v164, v165
	v_lshl_add_u64 v[164:165], v[154:155], 0, s[0:1]
	s_mov_b32 s0, 0x80000
	v_add_co_u32_e32 v166, vcc, s0, v154
	s_mov_b64 s[0:1], 0x90000
	s_nop 0
	v_addc_co_u32_e32 v167, vcc, 0, v155, vcc
	global_store_dwordx4 v[166:167], v[134:137], off
	s_waitcnt vmcnt(7)
	s_nop 0
	v_lshlrev_b32_e32 v134, 16, v138
	v_and_b32_e32 v135, 0xffff0000, v138
	v_lshlrev_b32_e32 v136, 16, v139
	v_and_b32_e32 v137, 0xffff0000, v139
	v_pk_mul_f32 v[134:135], v[30:31], v[134:135]
	v_pk_mul_f32 v[136:137], v[32:33], v[136:137]
	v_cvt_pk_bf16_f32 v134, v134, v135
	v_cvt_pk_bf16_f32 v135, v136, v137
	v_lshlrev_b32_e32 v136, 16, v140
	v_and_b32_e32 v137, 0xffff0000, v140
	v_lshlrev_b32_e32 v138, 16, v141
	v_and_b32_e32 v139, 0xffff0000, v141
	v_pk_mul_f32 v[136:137], v[26:27], v[136:137]
	v_pk_mul_f32 v[138:139], v[28:29], v[138:139]
	v_cvt_pk_bf16_f32 v136, v136, v137
	v_cvt_pk_bf16_f32 v137, v138, v139
	global_store_dwordx4 v[164:165], v[134:137], off offset:256
	s_waitcnt vmcnt(7)
	v_lshlrev_b32_e32 v138, 16, v145
	v_and_b32_e32 v139, 0xffff0000, v145
	v_lshlrev_b32_e32 v134, 16, v142
	v_and_b32_e32 v135, 0xffff0000, v142
	v_lshlrev_b32_e32 v136, 16, v143
	v_and_b32_e32 v137, 0xffff0000, v143
	v_pk_mul_f32 v[134:135], v[54:55], v[134:135]
	v_pk_mul_f32 v[136:137], v[56:57], v[136:137]
	v_cvt_pk_bf16_f32 v134, v134, v135
	v_cvt_pk_bf16_f32 v135, v136, v137
	v_lshlrev_b32_e32 v136, 16, v144
	v_and_b32_e32 v137, 0xffff0000, v144
	v_pk_mul_f32 v[136:137], v[50:51], v[136:137]
	v_pk_mul_f32 v[138:139], v[52:53], v[138:139]
	v_cvt_pk_bf16_f32 v136, v136, v137
	v_cvt_pk_bf16_f32 v137, v138, v139
	v_lshl_add_u64 v[138:139], v[154:155], 0, s[0:1]
	s_mov_b32 s0, 0x90000
	v_add_co_u32_e32 v140, vcc, s0, v154
	s_mov_b64 s[0:1], 0xa0000
	s_nop 0
	v_addc_co_u32_e32 v141, vcc, 0, v155, vcc
	global_store_dwordx4 v[140:141], v[134:137], off
	s_waitcnt vmcnt(7)
	v_lshlrev_b32_e32 v140, 16, v149
	v_and_b32_e32 v141, 0xffff0000, v149
	v_lshlrev_b32_e32 v134, 16, v146
	v_and_b32_e32 v135, 0xffff0000, v146
	v_lshlrev_b32_e32 v136, 16, v147
	v_and_b32_e32 v137, 0xffff0000, v147
	v_pk_mul_f32 v[134:135], v[22:23], v[134:135]
	v_pk_mul_f32 v[136:137], v[24:25], v[136:137]
	v_cvt_pk_bf16_f32 v134, v134, v135
	v_cvt_pk_bf16_f32 v135, v136, v137
	v_lshlrev_b32_e32 v136, 16, v148
	v_and_b32_e32 v137, 0xffff0000, v148
	v_pk_mul_f32 v[136:137], v[18:19], v[136:137]
	v_pk_mul_f32 v[140:141], v[20:21], v[140:141]
	v_cvt_pk_bf16_f32 v136, v136, v137
	v_cvt_pk_bf16_f32 v137, v140, v141
	global_store_dwordx4 v[138:139], v[134:137], off offset:256
	s_waitcnt vmcnt(7)
	v_lshlrev_b32_e32 v138, 16, v153
	v_and_b32_e32 v139, 0xffff0000, v153
	v_lshlrev_b32_e32 v134, 16, v150
	v_and_b32_e32 v135, 0xffff0000, v150
	v_lshlrev_b32_e32 v136, 16, v151
	v_and_b32_e32 v137, 0xffff0000, v151
	v_pk_mul_f32 v[134:135], v[46:47], v[134:135]
	v_pk_mul_f32 v[136:137], v[48:49], v[136:137]
	v_cvt_pk_bf16_f32 v134, v134, v135
	v_cvt_pk_bf16_f32 v135, v136, v137
	v_lshlrev_b32_e32 v136, 16, v152
	v_and_b32_e32 v137, 0xffff0000, v152
	v_pk_mul_f32 v[136:137], v[42:43], v[136:137]
	v_pk_mul_f32 v[138:139], v[44:45], v[138:139]
	v_cvt_pk_bf16_f32 v136, v136, v137
	v_cvt_pk_bf16_f32 v137, v138, v139
	v_lshl_add_u64 v[138:139], v[154:155], 0, s[0:1]
	s_mov_b32 s0, 0xa0000
	v_add_co_u32_e32 v140, vcc, s0, v154
	s_mov_b64 s[0:1], 0xb0000
	s_nop 0
	v_addc_co_u32_e32 v141, vcc, 0, v155, vcc
	global_store_dwordx4 v[140:141], v[134:137], off
	s_waitcnt vmcnt(7)
	v_lshlrev_b32_e32 v140, 16, v159
	v_and_b32_e32 v141, 0xffff0000, v159
	v_lshlrev_b32_e32 v134, 16, v156
	v_and_b32_e32 v135, 0xffff0000, v156
	v_lshlrev_b32_e32 v136, 16, v157
	v_and_b32_e32 v137, 0xffff0000, v157
	v_pk_mul_f32 v[134:135], v[14:15], v[134:135]
	v_pk_mul_f32 v[136:137], v[16:17], v[136:137]
	v_cvt_pk_bf16_f32 v134, v134, v135
	v_cvt_pk_bf16_f32 v135, v136, v137
	v_lshlrev_b32_e32 v136, 16, v158
	v_and_b32_e32 v137, 0xffff0000, v158
	v_pk_mul_f32 v[136:137], v[10:11], v[136:137]
	v_pk_mul_f32 v[140:141], v[12:13], v[140:141]
	v_cvt_pk_bf16_f32 v136, v136, v137
	v_cvt_pk_bf16_f32 v137, v140, v141
	global_store_dwordx4 v[138:139], v[134:137], off offset:256
	s_waitcnt vmcnt(7)
	v_lshlrev_b32_e32 v138, 16, v163
	v_and_b32_e32 v139, 0xffff0000, v163
	v_lshlrev_b32_e32 v134, 16, v160
	v_and_b32_e32 v135, 0xffff0000, v160
	v_lshlrev_b32_e32 v136, 16, v161
	v_and_b32_e32 v137, 0xffff0000, v161
	v_pk_mul_f32 v[134:135], v[38:39], v[134:135]
	v_pk_mul_f32 v[136:137], v[40:41], v[136:137]
	v_cvt_pk_bf16_f32 v134, v134, v135
	v_cvt_pk_bf16_f32 v135, v136, v137
	v_lshlrev_b32_e32 v136, 16, v162
	v_and_b32_e32 v137, 0xffff0000, v162
	v_pk_mul_f32 v[136:137], v[34:35], v[136:137]
	v_pk_mul_f32 v[138:139], v[36:37], v[138:139]
	v_cvt_pk_bf16_f32 v136, v136, v137
	v_cvt_pk_bf16_f32 v137, v138, v139
	v_lshl_add_u64 v[138:139], v[154:155], 0, s[0:1]
	s_mov_b32 s0, 0xb0000
	v_add_co_u32_e32 v140, vcc, s0, v154
	s_nop 1
	v_addc_co_u32_e32 v141, vcc, 0, v155, vcc
	global_store_dwordx4 v[140:141], v[134:137], off
	s_waitcnt vmcnt(7)
	s_nop 0
	v_lshlrev_b32_e32 v134, 16, v130
	v_and_b32_e32 v135, 0xffff0000, v130
	v_pk_mul_f32 v[134:135], v[6:7], v[134:135]
	s_nop 0
	v_cvt_pk_bf16_f32 v130, v134, v135
	v_lshlrev_b32_e32 v134, 16, v131
	v_and_b32_e32 v135, 0xffff0000, v131
	v_pk_mul_f32 v[134:135], v[8:9], v[134:135]
	s_nop 0
	v_cvt_pk_bf16_f32 v131, v134, v135
	v_lshlrev_b32_e32 v134, 16, v132
	v_and_b32_e32 v135, 0xffff0000, v132
	v_pk_mul_f32 v[134:135], v[2:3], v[134:135]
	s_nop 0
	v_cvt_pk_bf16_f32 v132, v134, v135
	v_lshlrev_b32_e32 v134, 16, v133
	v_and_b32_e32 v135, 0xffff0000, v133
	v_pk_mul_f32 v[134:135], v[4:5], v[134:135]
	s_nop 0
	v_cvt_pk_bf16_f32 v133, v134, v135
	global_store_dwordx4 v[138:139], v[130:133], off offset:256
	s_cbranch_execnz .LBB0_501
.LBB0_503:
	s_nop 0
	v_add_co_u32_e32 v130, vcc, 0x1000, v214
	s_mov_b32 s0, 0x120000
	s_nop 0
	v_addc_co_u32_e32 v131, vcc, 0, v215, vcc
	global_load_dwordx4 v[194:197], v[130:131], off nt
	global_load_dwordx4 v[178:181], v[214:215], off offset:256 nt
	global_load_dwordx4 v[182:185], v[130:131], off offset:256 nt
	v_add_co_u32_e32 v130, vcc, 0x90000, v214
	s_waitcnt vmcnt(2)
	v_lshlrev_b32_e32 v198, 16, v194
	v_addc_co_u32_e32 v131, vcc, 0, v215, vcc
	global_load_dwordx4 v[170:173], v[130:131], off nt
	v_add_co_u32_e32 v132, vcc, 0x91000, v214
	v_and_b32_e32 v194, 0xffff0000, v194
	s_nop 0
	v_addc_co_u32_e32 v133, vcc, 0, v215, vcc
	global_load_dwordx4 v[174:177], v[132:133], off nt
	global_load_dwordx4 v[162:165], v[130:131], off offset:256 nt
	global_load_dwordx4 v[166:169], v[132:133], off offset:256 nt
	v_add_co_u32_e32 v130, vcc, s0, v214
	s_mov_b32 s0, 0x121000
	s_nop 0
	v_addc_co_u32_e32 v131, vcc, 0, v215, vcc
	v_add_co_u32_e32 v134, vcc, s0, v214
	v_rcp_f32_e32 v198, v198
	v_rcp_f32_e32 v199, v194
	v_addc_co_u32_e32 v135, vcc, 0, v215, vcc
	global_load_dwordx4 v[154:157], v[134:135], off offset:-4096 nt
	global_load_dwordx4 v[158:161], v[134:135], off nt
	s_nop 0
	global_load_dwordx4 v[130:133], v[130:131], off offset:256 nt
	s_nop 0
	global_load_dwordx4 v[138:141], v[134:135], off offset:256 nt
	v_pk_mul_f32 v[192:193], v[198:199], v[192:193]
	s_mov_b32 s0, 0x1b0000
	v_pk_mul_f32 v[126:127], v[126:127], v[192:193]
	v_lshlrev_b32_e32 v192, 16, v195
	v_and_b32_e32 v193, 0xffff0000, v195
	v_rcp_f32_e32 v192, v192
	v_rcp_f32_e32 v193, v193
	v_add_co_u32_e32 v134, vcc, s0, v214
	s_mov_b32 s0, 0x1b1000
	v_pk_mul_f32 v[190:191], v[192:193], v[190:191]
	v_addc_co_u32_e32 v135, vcc, 0, v215, vcc
	v_pk_mul_f32 v[128:129], v[128:129], v[190:191]
	v_lshlrev_b32_e32 v190, 16, v196
	v_and_b32_e32 v191, 0xffff0000, v196
	v_rcp_f32_e32 v190, v190
	v_rcp_f32_e32 v191, v191
	v_add_co_u32_e32 v142, vcc, s0, v214
	s_mov_b32 s0, 0x480000
	v_pk_mul_f32 v[188:189], v[190:191], v[188:189]
	v_addc_co_u32_e32 v143, vcc, 0, v215, vcc
	v_pk_mul_f32 v[122:123], v[122:123], v[188:189]
	v_lshlrev_b32_e32 v188, 16, v197
	v_and_b32_e32 v189, 0xffff0000, v197
	v_rcp_f32_e32 v188, v188
	v_rcp_f32_e32 v189, v189
	global_load_dwordx4 v[146:149], v[142:143], off offset:-4096 nt
	global_load_dwordx4 v[150:153], v[142:143], off nt
	s_nop 0
	global_load_dwordx4 v[134:137], v[134:135], off offset:256 nt
	s_nop 0
	global_load_dwordx4 v[142:145], v[142:143], off offset:256 nt
	v_pk_mul_f32 v[186:187], v[188:189], v[186:187]
	s_nop 0
	v_pk_mul_f32 v[124:125], v[124:125], v[186:187]
	s_waitcnt vmcnt(12)
	v_lshlrev_b32_e32 v186, 16, v182
	v_and_b32_e32 v182, 0xffff0000, v182
	v_lshlrev_b32_e32 v188, 16, v178
	v_and_b32_e32 v189, 0xffff0000, v178
	v_lshlrev_b32_e32 v178, 16, v183
	v_rcp_f32_e32 v187, v182
	v_rcp_f32_e32 v182, v178
	v_and_b32_e32 v178, 0xffff0000, v183
	v_rcp_f32_e32 v183, v178
	v_lshlrev_b32_e32 v178, 16, v179
	v_and_b32_e32 v179, 0xffff0000, v179
	v_rcp_f32_e32 v186, v186
	v_pk_mul_f32 v[178:179], v[182:183], v[178:179]
	v_lshlrev_b32_e32 v182, 16, v180
	v_pk_mul_f32 v[96:97], v[96:97], v[178:179]
	v_lshlrev_b32_e32 v178, 16, v184
	v_and_b32_e32 v179, 0xffff0000, v184
	v_rcp_f32_e32 v178, v178
	v_rcp_f32_e32 v179, v179
	v_and_b32_e32 v183, 0xffff0000, v180
	v_lshlrev_b32_e32 v180, 16, v181
	v_and_b32_e32 v181, 0xffff0000, v181
	v_pk_mul_f32 v[178:179], v[178:179], v[182:183]
	v_pk_mul_f32 v[186:187], v[186:187], v[188:189]
	v_pk_mul_f32 v[90:91], v[90:91], v[178:179]
	v_lshlrev_b32_e32 v178, 16, v185
	v_and_b32_e32 v179, 0xffff0000, v185
	v_rcp_f32_e32 v178, v178
	v_rcp_f32_e32 v179, v179
	v_pk_mul_f32 v[94:95], v[94:95], v[186:187]
	v_pk_mul_f32 v[178:179], v[178:179], v[180:181]
	s_nop 0
	v_pk_mul_f32 v[92:93], v[92:93], v[178:179]
	s_waitcnt vmcnt(10)
	v_lshlrev_b32_e32 v178, 16, v174
	v_and_b32_e32 v174, 0xffff0000, v174
	v_lshlrev_b32_e32 v180, 16, v170
	v_and_b32_e32 v181, 0xffff0000, v170
	v_lshlrev_b32_e32 v170, 16, v175
	v_rcp_f32_e32 v179, v174
	v_rcp_f32_e32 v174, v170
	v_and_b32_e32 v170, 0xffff0000, v175
	v_rcp_f32_e32 v175, v170
	v_lshlrev_b32_e32 v170, 16, v171
	v_and_b32_e32 v171, 0xffff0000, v171
	v_rcp_f32_e32 v178, v178
	v_pk_mul_f32 v[170:171], v[174:175], v[170:171]
	v_lshlrev_b32_e32 v174, 16, v172
	v_pk_mul_f32 v[120:121], v[120:121], v[170:171]
	v_lshlrev_b32_e32 v170, 16, v176
	v_and_b32_e32 v171, 0xffff0000, v176
	v_rcp_f32_e32 v170, v170
	v_rcp_f32_e32 v171, v171
	v_and_b32_e32 v175, 0xffff0000, v172
	v_lshlrev_b32_e32 v172, 16, v173
	v_and_b32_e32 v173, 0xffff0000, v173
	v_pk_mul_f32 v[170:171], v[170:171], v[174:175]
	v_pk_mul_f32 v[178:179], v[178:179], v[180:181]
	v_pk_mul_f32 v[114:115], v[114:115], v[170:171]
	v_lshlrev_b32_e32 v170, 16, v177
	v_and_b32_e32 v171, 0xffff0000, v177
	v_rcp_f32_e32 v170, v170
	v_rcp_f32_e32 v171, v171
	v_pk_mul_f32 v[118:119], v[118:119], v[178:179]
	v_pk_mul_f32 v[170:171], v[170:171], v[172:173]
	s_nop 0
	v_pk_mul_f32 v[116:117], v[116:117], v[170:171]
	s_waitcnt vmcnt(8)
	v_lshlrev_b32_e32 v170, 16, v166
	v_and_b32_e32 v166, 0xffff0000, v166
	v_lshlrev_b32_e32 v172, 16, v162
	v_and_b32_e32 v173, 0xffff0000, v162
	v_lshlrev_b32_e32 v162, 16, v167
	v_rcp_f32_e32 v171, v166
	v_rcp_f32_e32 v166, v162
	v_and_b32_e32 v162, 0xffff0000, v167
	v_rcp_f32_e32 v167, v162
	v_lshlrev_b32_e32 v162, 16, v163
	v_and_b32_e32 v163, 0xffff0000, v163
	v_rcp_f32_e32 v170, v170
	v_pk_mul_f32 v[162:163], v[166:167], v[162:163]
	v_lshlrev_b32_e32 v166, 16, v164
	v_pk_mul_f32 v[88:89], v[88:89], v[162:163]
	v_lshlrev_b32_e32 v162, 16, v168
	v_and_b32_e32 v163, 0xffff0000, v168
	v_rcp_f32_e32 v162, v162
	v_rcp_f32_e32 v163, v163
	v_and_b32_e32 v167, 0xffff0000, v164
	v_lshlrev_b32_e32 v164, 16, v165
	v_and_b32_e32 v165, 0xffff0000, v165
	v_pk_mul_f32 v[162:163], v[162:163], v[166:167]
	v_pk_mul_f32 v[170:171], v[170:171], v[172:173]
	v_pk_mul_f32 v[82:83], v[82:83], v[162:163]
	v_lshlrev_b32_e32 v162, 16, v169
	v_and_b32_e32 v163, 0xffff0000, v169
	v_rcp_f32_e32 v162, v162
	v_rcp_f32_e32 v163, v163
	v_pk_mul_f32 v[86:87], v[86:87], v[170:171]
	v_pk_mul_f32 v[162:163], v[162:163], v[164:165]
	s_nop 0
	v_pk_mul_f32 v[84:85], v[84:85], v[162:163]
	s_waitcnt vmcnt(6)
	v_lshlrev_b32_e32 v162, 16, v158
	v_and_b32_e32 v158, 0xffff0000, v158
	v_lshlrev_b32_e32 v164, 16, v154
	v_and_b32_e32 v165, 0xffff0000, v154
	v_lshlrev_b32_e32 v154, 16, v159
	v_rcp_f32_e32 v163, v158
	v_rcp_f32_e32 v158, v154
	v_and_b32_e32 v154, 0xffff0000, v159
	v_rcp_f32_e32 v159, v154
	v_lshlrev_b32_e32 v154, 16, v155
	v_and_b32_e32 v155, 0xffff0000, v155
	v_rcp_f32_e32 v162, v162
	v_pk_mul_f32 v[154:155], v[158:159], v[154:155]
	v_lshlrev_b32_e32 v158, 16, v156
	v_pk_mul_f32 v[112:113], v[112:113], v[154:155]
	v_lshlrev_b32_e32 v154, 16, v160
	v_and_b32_e32 v155, 0xffff0000, v160
	v_rcp_f32_e32 v154, v154
	v_rcp_f32_e32 v155, v155
	v_and_b32_e32 v159, 0xffff0000, v156
	v_lshlrev_b32_e32 v156, 16, v157
	v_and_b32_e32 v157, 0xffff0000, v157
	v_pk_mul_f32 v[154:155], v[154:155], v[158:159]
	v_pk_mul_f32 v[162:163], v[162:163], v[164:165]
	v_pk_mul_f32 v[106:107], v[106:107], v[154:155]
	v_lshlrev_b32_e32 v154, 16, v161
	v_and_b32_e32 v155, 0xffff0000, v161
	v_rcp_f32_e32 v154, v154
	v_rcp_f32_e32 v155, v155
	v_pk_mul_f32 v[110:111], v[110:111], v[162:163]
	v_pk_mul_f32 v[154:155], v[154:155], v[156:157]
	s_nop 0
	v_pk_mul_f32 v[108:109], v[108:109], v[154:155]
	s_waitcnt vmcnt(4)
	v_lshlrev_b32_e32 v154, 16, v138
	v_and_b32_e32 v138, 0xffff0000, v138
	v_lshlrev_b32_e32 v156, 16, v130
	v_and_b32_e32 v157, 0xffff0000, v130
	v_lshlrev_b32_e32 v130, 16, v139
	v_rcp_f32_e32 v155, v138
	v_rcp_f32_e32 v138, v130
	v_and_b32_e32 v130, 0xffff0000, v139
	v_rcp_f32_e32 v139, v130
	v_lshlrev_b32_e32 v130, 16, v131
	v_and_b32_e32 v131, 0xffff0000, v131
	v_rcp_f32_e32 v154, v154
	v_pk_mul_f32 v[130:131], v[138:139], v[130:131]
	v_lshlrev_b32_e32 v138, 16, v132
	v_pk_mul_f32 v[80:81], v[80:81], v[130:131]
	v_lshlrev_b32_e32 v130, 16, v140
	v_and_b32_e32 v131, 0xffff0000, v140
	v_rcp_f32_e32 v130, v130
	v_rcp_f32_e32 v131, v131
	v_and_b32_e32 v139, 0xffff0000, v132
	v_lshlrev_b32_e32 v132, 16, v133
	v_and_b32_e32 v133, 0xffff0000, v133
	v_pk_mul_f32 v[130:131], v[130:131], v[138:139]
	v_pk_mul_f32 v[154:155], v[154:155], v[156:157]
	v_pk_mul_f32 v[74:75], v[74:75], v[130:131]
	v_lshlrev_b32_e32 v130, 16, v141
	v_and_b32_e32 v131, 0xffff0000, v141
	v_rcp_f32_e32 v130, v130
	v_rcp_f32_e32 v131, v131
	v_pk_mul_f32 v[78:79], v[78:79], v[154:155]
	v_pk_mul_f32 v[130:131], v[130:131], v[132:133]
	s_nop 0
	v_pk_mul_f32 v[76:77], v[76:77], v[130:131]
	s_waitcnt vmcnt(2)
	v_lshlrev_b32_e32 v130, 16, v150
	v_and_b32_e32 v131, 0xffff0000, v150
	v_rcp_f32_e32 v130, v130
	v_rcp_f32_e32 v131, v131
	v_lshlrev_b32_e32 v132, 16, v146
	v_and_b32_e32 v133, 0xffff0000, v146
	v_pk_mul_f32 v[130:131], v[130:131], v[132:133]
	s_nop 0
	v_pk_mul_f32 v[102:103], v[102:103], v[130:131]
	v_lshlrev_b32_e32 v130, 16, v151
	v_and_b32_e32 v131, 0xffff0000, v151
	v_rcp_f32_e32 v130, v130
	v_rcp_f32_e32 v131, v131
	v_lshlrev_b32_e32 v132, 16, v147
	v_and_b32_e32 v133, 0xffff0000, v147
	v_pk_mul_f32 v[130:131], v[130:131], v[132:133]
	s_nop 0
	v_pk_mul_f32 v[104:105], v[104:105], v[130:131]
	v_lshlrev_b32_e32 v130, 16, v152
	v_and_b32_e32 v131, 0xffff0000, v152
	v_rcp_f32_e32 v130, v130
	v_rcp_f32_e32 v131, v131
	v_lshlrev_b32_e32 v132, 16, v148
	v_and_b32_e32 v133, 0xffff0000, v148
	v_pk_mul_f32 v[130:131], v[130:131], v[132:133]
	s_nop 0
	v_pk_mul_f32 v[98:99], v[98:99], v[130:131]
	v_lshlrev_b32_e32 v130, 16, v153
	v_and_b32_e32 v131, 0xffff0000, v153
	v_rcp_f32_e32 v130, v130
	v_rcp_f32_e32 v131, v131
	v_lshlrev_b32_e32 v132, 16, v149
	v_and_b32_e32 v133, 0xffff0000, v149
	v_pk_mul_f32 v[130:131], v[130:131], v[132:133]
	s_nop 0
	v_pk_mul_f32 v[100:101], v[100:101], v[130:131]
	s_waitcnt vmcnt(0)
	v_lshlrev_b32_e32 v130, 16, v142
	v_and_b32_e32 v131, 0xffff0000, v142
	v_rcp_f32_e32 v130, v130
	v_rcp_f32_e32 v131, v131
	v_lshlrev_b32_e32 v132, 16, v134
	v_and_b32_e32 v133, 0xffff0000, v134
	v_pk_mul_f32 v[130:131], v[130:131], v[132:133]
	s_nop 0
	v_pk_mul_f32 v[70:71], v[70:71], v[130:131]
	v_lshlrev_b32_e32 v130, 16, v143
	v_and_b32_e32 v131, 0xffff0000, v143
	v_rcp_f32_e32 v130, v130
	v_rcp_f32_e32 v131, v131
	v_lshlrev_b32_e32 v132, 16, v135
	v_and_b32_e32 v133, 0xffff0000, v135
	v_pk_mul_f32 v[130:131], v[130:131], v[132:133]
	s_nop 0
	v_pk_mul_f32 v[72:73], v[72:73], v[130:131]
	v_lshlrev_b32_e32 v130, 16, v144
	v_and_b32_e32 v131, 0xffff0000, v144
	v_rcp_f32_e32 v130, v130
	v_rcp_f32_e32 v131, v131
	v_lshlrev_b32_e32 v132, 16, v136
	v_and_b32_e32 v133, 0xffff0000, v136
	v_pk_mul_f32 v[130:131], v[130:131], v[132:133]
	s_nop 0
	v_pk_mul_f32 v[66:67], v[66:67], v[130:131]
	v_lshlrev_b32_e32 v130, 16, v145
	v_and_b32_e32 v131, 0xffff0000, v145
	v_rcp_f32_e32 v130, v130
	v_rcp_f32_e32 v131, v131
	v_lshlrev_b32_e32 v132, 16, v137
	v_and_b32_e32 v133, 0xffff0000, v137
	v_pk_mul_f32 v[130:131], v[130:131], v[132:133]
	s_nop 0
	v_pk_mul_f32 v[68:69], v[68:69], v[130:131]
	v_add_co_u32_e32 v130, vcc, s0, v214
	s_mov_b32 s0, 0x481000
	s_nop 0
	v_addc_co_u32_e32 v131, vcc, 0, v215, vcc
	v_add_co_u32_e32 v132, vcc, s0, v214
	s_mov_b32 s0, 0x510000
	s_nop 0
	v_addc_co_u32_e32 v133, vcc, 0, v215, vcc
	global_load_dwordx4 v[174:177], v[132:133], off offset:-4096 nt
	global_load_dwordx4 v[178:181], v[132:133], off nt
	global_load_dwordx4 v[162:165], v[130:131], off offset:256 nt
	global_load_dwordx4 v[190:193], v[132:133], off offset:256 nt
	v_add_co_u32_e32 v130, vcc, s0, v214
	s_mov_b32 s0, 0x511000
	s_nop 0
	v_addc_co_u32_e32 v131, vcc, 0, v215, vcc
	v_add_co_u32_e32 v132, vcc, s0, v214
	s_mov_b32 s0, 0x5a0000
	s_nop 0
	v_addc_co_u32_e32 v133, vcc, 0, v215, vcc
	global_load_dwordx4 v[182:185], v[132:133], off offset:-4096 nt
	global_load_dwordx4 v[186:189], v[132:133], off nt
	global_load_dwordx4 v[166:169], v[130:131], off offset:256 nt
	global_load_dwordx4 v[170:173], v[132:133], off offset:256 nt
	v_add_co_u32_e32 v130, vcc, s0, v214
	s_mov_b32 s0, 0x5a1000
	s_nop 0
	v_addc_co_u32_e32 v131, vcc, 0, v215, vcc
	v_add_co_u32_e32 v132, vcc, s0, v214
	s_mov_b32 s0, 0x630000
	s_nop 0
	v_addc_co_u32_e32 v133, vcc, 0, v215, vcc
	global_load_dwordx4 v[154:157], v[132:133], off offset:-4096 nt
	global_load_dwordx4 v[158:161], v[132:133], off nt
	global_load_dwordx4 v[146:149], v[130:131], off offset:256 nt
	global_load_dwordx4 v[150:153], v[132:133], off offset:256 nt
	v_add_co_u32_e32 v130, vcc, s0, v214
	s_mov_b32 s0, 0x631000
	s_nop 0
	v_addc_co_u32_e32 v131, vcc, 0, v215, vcc
	v_add_co_u32_e32 v134, vcc, s0, v214
	s_waitcnt vmcnt(11)
	v_lshlrev_b32_e32 v196, 16, v174
	s_waitcnt vmcnt(10)
	v_lshlrev_b32_e32 v194, 16, v178
	v_and_b32_e32 v178, 0xffff0000, v178
	v_and_b32_e32 v197, 0xffff0000, v174
	v_lshlrev_b32_e32 v174, 16, v179
	v_rcp_f32_e32 v195, v178
	v_rcp_f32_e32 v178, v174
	v_and_b32_e32 v174, 0xffff0000, v179
	v_rcp_f32_e32 v179, v174
	v_lshlrev_b32_e32 v174, 16, v175
	v_and_b32_e32 v175, 0xffff0000, v175
	v_addc_co_u32_e32 v135, vcc, 0, v215, vcc
	v_pk_mul_f32 v[174:175], v[178:179], v[174:175]
	v_lshlrev_b32_e32 v178, 16, v176
	v_pk_mul_f32 v[64:65], v[64:65], v[174:175]
	v_lshlrev_b32_e32 v174, 16, v180
	v_and_b32_e32 v175, 0xffff0000, v180
	v_rcp_f32_e32 v174, v174
	v_rcp_f32_e32 v175, v175
	v_and_b32_e32 v179, 0xffff0000, v176
	v_lshlrev_b32_e32 v176, 16, v177
	v_and_b32_e32 v177, 0xffff0000, v177
	v_pk_mul_f32 v[174:175], v[174:175], v[178:179]
	global_load_dwordx4 v[138:141], v[134:135], off offset:-4096 nt
	global_load_dwordx4 v[142:145], v[134:135], off nt
	s_nop 0
	global_load_dwordx4 v[130:133], v[130:131], off offset:256 nt
	s_nop 0
	global_load_dwordx4 v[134:137], v[134:135], off offset:256 nt
	v_pk_mul_f32 v[58:59], v[58:59], v[174:175]
	v_lshlrev_b32_e32 v174, 16, v181
	v_and_b32_e32 v175, 0xffff0000, v181
	v_rcp_f32_e32 v174, v174
	v_rcp_f32_e32 v175, v175
	v_rcp_f32_e32 v194, v194
	v_pk_mul_f32 v[174:175], v[174:175], v[176:177]
	s_nop 0
	v_pk_mul_f32 v[60:61], v[60:61], v[174:175]
	s_waitcnt vmcnt(12)
	v_lshlrev_b32_e32 v174, 16, v190
	v_and_b32_e32 v175, 0xffff0000, v190
	v_rcp_f32_e32 v174, v174
	v_rcp_f32_e32 v175, v175
	v_lshlrev_b32_e32 v176, 16, v162
	v_and_b32_e32 v177, 0xffff0000, v162
	v_lshlrev_b32_e32 v162, 16, v191
	v_pk_mul_f32 v[174:175], v[174:175], v[176:177]
	v_pk_mul_f32 v[194:195], v[194:195], v[196:197]
	v_pk_mul_f32 v[30:31], v[30:31], v[174:175]
	v_rcp_f32_e32 v174, v162
	v_and_b32_e32 v162, 0xffff0000, v191
	v_rcp_f32_e32 v175, v162
	v_lshlrev_b32_e32 v162, 16, v163
	v_and_b32_e32 v163, 0xffff0000, v163
	v_pk_mul_f32 v[62:63], v[62:63], v[194:195]
	v_pk_mul_f32 v[162:163], v[174:175], v[162:163]
	v_lshlrev_b32_e32 v174, 16, v164
	v_pk_mul_f32 v[32:33], v[32:33], v[162:163]
	v_lshlrev_b32_e32 v162, 16, v192
	v_and_b32_e32 v163, 0xffff0000, v192
	v_rcp_f32_e32 v162, v162
	v_rcp_f32_e32 v163, v163
	v_and_b32_e32 v175, 0xffff0000, v164
	v_lshlrev_b32_e32 v164, 16, v165
	v_and_b32_e32 v165, 0xffff0000, v165
	v_pk_mul_f32 v[162:163], v[162:163], v[174:175]
	s_nop 0
	v_pk_mul_f32 v[26:27], v[26:27], v[162:163]
	v_lshlrev_b32_e32 v162, 16, v193
	v_and_b32_e32 v163, 0xffff0000, v193
	v_rcp_f32_e32 v162, v162
	v_rcp_f32_e32 v163, v163
	s_nop 0
	v_pk_mul_f32 v[162:163], v[162:163], v[164:165]
	s_nop 0
	v_pk_mul_f32 v[28:29], v[28:29], v[162:163]
	s_waitcnt vmcnt(10)
	v_lshlrev_b32_e32 v162, 16, v186
	v_and_b32_e32 v163, 0xffff0000, v186
	v_rcp_f32_e32 v162, v162
	v_rcp_f32_e32 v163, v163
	v_lshlrev_b32_e32 v164, 16, v182
	v_and_b32_e32 v165, 0xffff0000, v182
	v_pk_mul_f32 v[162:163], v[162:163], v[164:165]
	s_nop 0
	v_pk_mul_f32 v[54:55], v[54:55], v[162:163]
	v_lshlrev_b32_e32 v162, 16, v187
	v_and_b32_e32 v163, 0xffff0000, v187
	v_rcp_f32_e32 v162, v162
	v_rcp_f32_e32 v163, v163
	v_lshlrev_b32_e32 v164, 16, v183
	v_and_b32_e32 v165, 0xffff0000, v183
	v_pk_mul_f32 v[162:163], v[162:163], v[164:165]
	s_nop 0
	v_pk_mul_f32 v[56:57], v[56:57], v[162:163]
	v_lshlrev_b32_e32 v162, 16, v188
	v_and_b32_e32 v163, 0xffff0000, v188
	v_rcp_f32_e32 v162, v162
	v_rcp_f32_e32 v163, v163
	v_lshlrev_b32_e32 v164, 16, v184
	v_and_b32_e32 v165, 0xffff0000, v184
	v_pk_mul_f32 v[162:163], v[162:163], v[164:165]
	s_nop 0
	v_pk_mul_f32 v[50:51], v[50:51], v[162:163]
	v_lshlrev_b32_e32 v162, 16, v189
	v_and_b32_e32 v163, 0xffff0000, v189
	v_rcp_f32_e32 v162, v162
	v_rcp_f32_e32 v163, v163
	v_lshlrev_b32_e32 v164, 16, v185
	v_and_b32_e32 v165, 0xffff0000, v185
	v_pk_mul_f32 v[162:163], v[162:163], v[164:165]
	s_nop 0
	v_pk_mul_f32 v[52:53], v[52:53], v[162:163]
	s_waitcnt vmcnt(8)
	v_lshlrev_b32_e32 v162, 16, v170
	v_and_b32_e32 v163, 0xffff0000, v170
	v_rcp_f32_e32 v162, v162
	v_rcp_f32_e32 v163, v163
	v_lshlrev_b32_e32 v164, 16, v166
	v_and_b32_e32 v165, 0xffff0000, v166
	v_pk_mul_f32 v[162:163], v[162:163], v[164:165]
	s_nop 0
	v_pk_mul_f32 v[22:23], v[22:23], v[162:163]
	v_lshlrev_b32_e32 v162, 16, v171
	v_and_b32_e32 v163, 0xffff0000, v171
	v_rcp_f32_e32 v162, v162
	v_rcp_f32_e32 v163, v163
	v_lshlrev_b32_e32 v164, 16, v167
	v_and_b32_e32 v165, 0xffff0000, v167
	v_pk_mul_f32 v[162:163], v[162:163], v[164:165]
	s_nop 0
	v_pk_mul_f32 v[24:25], v[24:25], v[162:163]
	v_lshlrev_b32_e32 v162, 16, v172
	v_and_b32_e32 v163, 0xffff0000, v172
	v_rcp_f32_e32 v162, v162
	v_rcp_f32_e32 v163, v163
	v_lshlrev_b32_e32 v164, 16, v168
	v_and_b32_e32 v165, 0xffff0000, v168
	v_pk_mul_f32 v[162:163], v[162:163], v[164:165]
	s_nop 0
	v_pk_mul_f32 v[18:19], v[18:19], v[162:163]
	v_lshlrev_b32_e32 v162, 16, v173
	v_and_b32_e32 v163, 0xffff0000, v173
	v_rcp_f32_e32 v162, v162
	v_rcp_f32_e32 v163, v163
	v_lshlrev_b32_e32 v164, 16, v169
	v_and_b32_e32 v165, 0xffff0000, v169
	v_pk_mul_f32 v[162:163], v[162:163], v[164:165]
	s_nop 0
	v_pk_mul_f32 v[20:21], v[20:21], v[162:163]
	s_waitcnt vmcnt(6)
	v_lshlrev_b32_e32 v162, 16, v158
	v_and_b32_e32 v158, 0xffff0000, v158
	v_lshlrev_b32_e32 v164, 16, v154
	v_and_b32_e32 v165, 0xffff0000, v154
	v_lshlrev_b32_e32 v154, 16, v159
	v_rcp_f32_e32 v163, v158
	v_rcp_f32_e32 v158, v154
	v_and_b32_e32 v154, 0xffff0000, v159
	v_rcp_f32_e32 v159, v154
	v_lshlrev_b32_e32 v154, 16, v155
	v_and_b32_e32 v155, 0xffff0000, v155
	v_rcp_f32_e32 v162, v162
	v_pk_mul_f32 v[154:155], v[158:159], v[154:155]
	v_lshlrev_b32_e32 v158, 16, v156
	v_pk_mul_f32 v[48:49], v[48:49], v[154:155]
	v_lshlrev_b32_e32 v154, 16, v160
	v_and_b32_e32 v155, 0xffff0000, v160
	v_rcp_f32_e32 v154, v154
	v_rcp_f32_e32 v155, v155
	v_and_b32_e32 v159, 0xffff0000, v156
	v_lshlrev_b32_e32 v156, 16, v157
	v_and_b32_e32 v157, 0xffff0000, v157
	v_pk_mul_f32 v[154:155], v[154:155], v[158:159]
	v_pk_mul_f32 v[162:163], v[162:163], v[164:165]
	v_pk_mul_f32 v[42:43], v[42:43], v[154:155]
	v_lshlrev_b32_e32 v154, 16, v161
	v_and_b32_e32 v155, 0xffff0000, v161
	v_rcp_f32_e32 v154, v154
	v_rcp_f32_e32 v155, v155
	v_pk_mul_f32 v[46:47], v[46:47], v[162:163]
	v_pk_mul_f32 v[154:155], v[154:155], v[156:157]
	s_nop 0
	v_pk_mul_f32 v[44:45], v[44:45], v[154:155]
	s_waitcnt vmcnt(4)
	v_lshlrev_b32_e32 v154, 16, v150
	v_and_b32_e32 v150, 0xffff0000, v150
	v_lshlrev_b32_e32 v156, 16, v146
	v_and_b32_e32 v157, 0xffff0000, v146
	v_lshlrev_b32_e32 v146, 16, v151
	v_rcp_f32_e32 v155, v150
	v_rcp_f32_e32 v150, v146
	v_and_b32_e32 v146, 0xffff0000, v151
	v_rcp_f32_e32 v151, v146
	v_lshlrev_b32_e32 v146, 16, v147
	v_and_b32_e32 v147, 0xffff0000, v147
	v_rcp_f32_e32 v154, v154
	v_pk_mul_f32 v[146:147], v[150:151], v[146:147]
	v_lshlrev_b32_e32 v150, 16, v148
	v_pk_mul_f32 v[16:17], v[16:17], v[146:147]
	v_lshlrev_b32_e32 v146, 16, v152
	v_and_b32_e32 v147, 0xffff0000, v152
	v_rcp_f32_e32 v146, v146
	v_rcp_f32_e32 v147, v147
	v_and_b32_e32 v151, 0xffff0000, v148
	v_lshlrev_b32_e32 v148, 16, v149
	v_and_b32_e32 v149, 0xffff0000, v149
	v_pk_mul_f32 v[146:147], v[146:147], v[150:151]
	v_pk_mul_f32 v[154:155], v[154:155], v[156:157]
	v_pk_mul_f32 v[10:11], v[10:11], v[146:147]
	v_lshlrev_b32_e32 v146, 16, v153
	v_and_b32_e32 v147, 0xffff0000, v153
	v_rcp_f32_e32 v146, v146
	v_rcp_f32_e32 v147, v147
	v_pk_mul_f32 v[14:15], v[14:15], v[154:155]
	v_pk_mul_f32 v[146:147], v[146:147], v[148:149]
	s_nop 0
	v_pk_mul_f32 v[12:13], v[12:13], v[146:147]
	s_waitcnt vmcnt(2)
	v_lshlrev_b32_e32 v146, 16, v142
	v_and_b32_e32 v142, 0xffff0000, v142
	v_lshlrev_b32_e32 v148, 16, v138
	v_and_b32_e32 v149, 0xffff0000, v138
	v_lshlrev_b32_e32 v138, 16, v143
	v_rcp_f32_e32 v147, v142
	v_rcp_f32_e32 v142, v138
	v_and_b32_e32 v138, 0xffff0000, v143
	v_rcp_f32_e32 v143, v138
	v_lshlrev_b32_e32 v138, 16, v139
	v_and_b32_e32 v139, 0xffff0000, v139
	v_rcp_f32_e32 v146, v146
	v_pk_mul_f32 v[138:139], v[142:143], v[138:139]
	v_lshlrev_b32_e32 v142, 16, v140
	v_pk_mul_f32 v[40:41], v[40:41], v[138:139]
	v_lshlrev_b32_e32 v138, 16, v144
	v_and_b32_e32 v139, 0xffff0000, v144
	v_rcp_f32_e32 v138, v138
	v_rcp_f32_e32 v139, v139
	v_and_b32_e32 v143, 0xffff0000, v140
	v_lshlrev_b32_e32 v140, 16, v141
	v_and_b32_e32 v141, 0xffff0000, v141
	v_pk_mul_f32 v[138:139], v[138:139], v[142:143]
	v_pk_mul_f32 v[146:147], v[146:147], v[148:149]
	v_pk_mul_f32 v[34:35], v[34:35], v[138:139]
	v_lshlrev_b32_e32 v138, 16, v145
	v_and_b32_e32 v139, 0xffff0000, v145
	v_rcp_f32_e32 v138, v138
	v_rcp_f32_e32 v139, v139
	v_pk_mul_f32 v[38:39], v[38:39], v[146:147]
	v_pk_mul_f32 v[138:139], v[138:139], v[140:141]
	s_nop 0
	v_pk_mul_f32 v[36:37], v[36:37], v[138:139]
	s_waitcnt vmcnt(0)
	v_lshlrev_b32_e32 v138, 16, v134
	v_and_b32_e32 v134, 0xffff0000, v134
	v_lshlrev_b32_e32 v140, 16, v130
	v_and_b32_e32 v141, 0xffff0000, v130
	v_lshlrev_b32_e32 v130, 16, v135
	v_rcp_f32_e32 v139, v134
	v_rcp_f32_e32 v134, v130
	v_and_b32_e32 v130, 0xffff0000, v135
	v_rcp_f32_e32 v135, v130
	v_lshlrev_b32_e32 v130, 16, v131
	v_and_b32_e32 v131, 0xffff0000, v131
	v_rcp_f32_e32 v138, v138
	v_pk_mul_f32 v[130:131], v[134:135], v[130:131]
	v_lshlrev_b32_e32 v134, 16, v132
	v_pk_mul_f32 v[8:9], v[8:9], v[130:131]
	v_lshlrev_b32_e32 v130, 16, v136
	v_and_b32_e32 v131, 0xffff0000, v136
	v_rcp_f32_e32 v130, v130
	v_rcp_f32_e32 v131, v131
	v_and_b32_e32 v135, 0xffff0000, v132
	v_lshlrev_b32_e32 v132, 16, v133
	v_and_b32_e32 v133, 0xffff0000, v133
	v_pk_mul_f32 v[130:131], v[130:131], v[134:135]
	v_pk_mul_f32 v[138:139], v[138:139], v[140:141]
	v_pk_mul_f32 v[2:3], v[2:3], v[130:131]
	v_lshlrev_b32_e32 v130, 16, v137
	v_and_b32_e32 v131, 0xffff0000, v137
	v_rcp_f32_e32 v130, v130
	v_rcp_f32_e32 v131, v131
	v_pk_mul_f32 v[6:7], v[6:7], v[138:139]
	v_pk_mul_f32 v[130:131], v[130:131], v[132:133]
	s_nop 0
	v_pk_mul_f32 v[4:5], v[4:5], v[130:131]
	s_andn2_b64 vcc, exec, s[8:9]
	s_mov_b64 s[0:1], -1
	s_cbranch_vccnz .LBB0_488

.LBB0_583:
	s_lshl_b32 s0, s5, 8
	v_readlane_b32 s1, v254, 61
	v_mbcnt_lo_u32_b32 v131, -1, 0
	v_mbcnt_hi_u32_b32 v131, -1, v131
	s_add_i32 s0, s0, s1
	v_and_or_b32 v130, v131, 15, s0
	s_lshl_b32 s0, s4, 8
	v_ashrrev_i32_e32 v131, 1, v131
	v_and_b32_e32 v131, -8, v131
	s_or_b32 s0, s0, s81
	v_add_u32_e32 v132, s0, v131
	v_ashrrev_i32_e32 v133, 31, v132
	v_lshlrev_b64 v[152:153], 2, v[132:133]
	v_ashrrev_i32_e32 v131, 31, v130
	v_lshl_add_u64 v[154:155], s[8:9], 0, v[152:153]
	v_lshlrev_b64 v[156:157], 13, v[130:131]
	v_lshl_add_u64 v[132:133], v[154:155], 0, v[156:157]
	global_load_dwordx4 v[162:165], v[132:133], off offset:16 nt
	global_load_dwordx4 v[166:169], v[132:133], off nt
	global_load_dwordx4 v[170:173], v[132:133], off offset:528 nt
	global_load_dwordx4 v[174:177], v[132:133], off offset:512 nt
	v_or_b32_e32 v132, 16, v130
	v_ashrrev_i32_e32 v133, 31, v132
	v_lshlrev_b64 v[198:199], 13, v[132:133]
	v_lshl_add_u64 v[132:133], v[154:155], 0, v[198:199]
	global_load_dwordx4 v[178:181], v[132:133], off offset:16 nt
	global_load_dwordx4 v[182:185], v[132:133], off nt
	global_load_dwordx4 v[186:189], v[132:133], off offset:528 nt
	global_load_dwordx4 v[190:193], v[132:133], off offset:512 nt
	v_or_b32_e32 v132, 32, v130
	v_ashrrev_i32_e32 v133, 31, v132
	v_lshlrev_b64 v[220:221], 13, v[132:133]
	v_or_b32_e32 v130, 48, v130
	v_lshl_add_u64 v[132:133], v[154:155], 0, v[220:221]
	v_ashrrev_i32_e32 v131, 31, v130
	global_load_dwordx4 v[194:197], v[132:133], off offset:16 nt
	global_load_dwordx4 v[204:207], v[132:133], off nt
	global_load_dwordx4 v[208:211], v[132:133], off offset:528 nt
	global_load_dwordx4 v[212:215], v[132:133], off offset:512 nt
	v_lshlrev_b64 v[158:159], 13, v[130:131]
	v_lshl_add_u64 v[138:139], v[154:155], 0, v[158:159]
	global_load_dwordx4 v[134:137], v[138:139], off offset:16 nt
	global_load_dwordx4 v[216:219], v[138:139], off nt
	global_load_dwordx4 v[130:133], v[138:139], off offset:528 nt
	s_nop 0
	global_load_dwordx4 v[138:141], v[138:139], off offset:512 nt
	s_mov_b64 s[0:1], 0x100000
	s_andn2_b64 vcc, exec, s[6:7]
	s_waitcnt vmcnt(0)
	v_pk_add_f32 v[124:125], v[124:125], v[164:165]
	v_pk_add_f32 v[126:127], v[126:127], v[166:167]
	v_lshl_add_u64 v[166:167], s[10:11], 0, v[156:157]
	v_lshl_add_u64 v[166:167], v[166:167], 0, v[152:153]
	v_pk_add_f32 v[116:117], v[116:117], v[176:177]
	v_pk_add_f32 v[114:115], v[114:115], v[174:175]
	global_store_dwordx4 v[166:167], v[114:117], off offset:512
	v_pk_add_f32 v[112:113], v[112:113], v[172:173]
	v_pk_add_f32 v[100:101], v[100:101], v[192:193]
	v_lshl_add_u64 v[114:115], s[10:11], 0, v[198:199]
	v_lshl_add_u64 v[114:115], v[114:115], 0, v[152:153]
	v_pk_add_f32 v[98:99], v[98:99], v[190:191]
	global_store_dwordx4 v[114:115], v[98:101], off offset:512
	v_pk_add_f32 v[110:111], v[110:111], v[170:171]
	v_pk_add_f32 v[96:97], v[96:97], v[188:189]
	v_lshl_add_u64 v[98:99], s[10:11], 0, v[220:221]
	v_lshl_add_u64 v[98:99], v[98:99], 0, v[152:153]
	v_pk_add_f32 v[84:85], v[84:85], v[214:215]
	v_pk_add_f32 v[82:83], v[82:83], v[212:213]
	v_pk_add_f32 v[94:95], v[94:95], v[186:187]
	global_store_dwordx4 v[98:99], v[82:85], off offset:512
	v_pk_add_f32 v[80:81], v[80:81], v[210:211]
	v_pk_add_f32 v[78:79], v[78:79], v[208:209]
	v_lshl_add_u64 v[82:83], s[10:11], 0, v[158:159]
	v_pk_add_f32 v[128:129], v[128:129], v[168:169]
	v_pk_add_f32 v[122:123], v[122:123], v[162:163]
	global_store_dwordx4 v[166:167], v[110:113], off offset:528
	v_pk_add_f32 v[108:109], v[108:109], v[180:181]
	v_pk_add_f32 v[106:107], v[106:107], v[178:179]
	v_pk_add_f32 v[112:113], v[120:121], v[184:185]
	v_pk_add_f32 v[110:111], v[118:119], v[182:183]
	global_store_dwordx4 v[114:115], v[94:97], off offset:528
	v_pk_add_f32 v[92:93], v[92:93], v[196:197]
	v_pk_add_f32 v[90:91], v[90:91], v[194:195]
	v_pk_add_f32 v[96:97], v[104:105], v[206:207]
	v_pk_add_f32 v[94:95], v[102:103], v[204:205]
	global_store_dwordx4 v[98:99], v[78:81], off offset:528
	v_lshl_add_u64 v[82:83], v[82:83], 0, v[152:153]
	v_pk_add_f32 v[76:77], v[76:77], v[136:137]
	v_pk_add_f32 v[80:81], v[88:89], v[218:219]
	v_pk_add_f32 v[78:79], v[86:87], v[216:217]
	v_pk_add_f32 v[74:75], v[74:75], v[134:135]
	v_pk_add_f32 v[72:73], v[72:73], v[140:141]
	v_pk_add_f32 v[70:71], v[70:71], v[138:139]
	v_pk_add_f32 v[68:69], v[68:69], v[132:133]
	v_pk_add_f32 v[66:67], v[66:67], v[130:131]
	global_store_dwordx4 v[166:167], v[126:129], off
	global_store_dwordx4 v[166:167], v[122:125], off offset:16
	global_store_dwordx4 v[114:115], v[110:113], off
	global_store_dwordx4 v[114:115], v[106:109], off offset:16
	global_store_dwordx4 v[98:99], v[94:97], off
	global_store_dwordx4 v[98:99], v[90:93], off offset:16
	global_store_dwordx4 v[82:83], v[78:81], off
	global_store_dwordx4 v[82:83], v[74:77], off offset:16
	global_store_dwordx4 v[82:83], v[70:73], off offset:512
	global_store_dwordx4 v[82:83], v[66:69], off offset:528
	v_lshl_add_u64 v[134:135], v[156:157], 0, s[0:1]
	s_mov_b64 s[0:1], 0x120000
	v_lshl_add_u64 v[66:67], v[154:155], 0, v[134:135]
	global_load_dwordx4 v[98:101], v[66:67], off offset:16 nt
	global_load_dwordx4 v[102:105], v[66:67], off nt
	global_load_dwordx4 v[106:109], v[66:67], off offset:528 nt
	global_load_dwordx4 v[110:113], v[66:67], off offset:512 nt
	v_lshl_add_u64 v[136:137], v[156:157], 0, s[0:1]
	v_lshl_add_u64 v[66:67], v[154:155], 0, v[136:137]
	s_mov_b64 s[0:1], 0x140000
	global_load_dwordx4 v[114:117], v[66:67], off offset:16 nt
	global_load_dwordx4 v[118:121], v[66:67], off nt
	global_load_dwordx4 v[122:125], v[66:67], off offset:528 nt
	global_load_dwordx4 v[126:129], v[66:67], off offset:512 nt
	v_lshl_add_u64 v[96:97], v[156:157], 0, s[0:1]
	v_lshl_add_u64 v[66:67], v[154:155], 0, v[96:97]
	s_mov_b64 s[0:1], 0x160000
	global_load_dwordx4 v[82:85], v[66:67], off offset:16 nt
	global_load_dwordx4 v[130:133], v[66:67], off nt
	global_load_dwordx4 v[78:81], v[66:67], off offset:528 nt
	global_load_dwordx4 v[90:93], v[66:67], off offset:512 nt
	v_lshl_add_u64 v[94:95], v[156:157], 0, s[0:1]
	v_lshl_add_u64 v[70:71], v[154:155], 0, v[94:95]
	global_load_dwordx4 v[74:77], v[70:71], off offset:16 nt
	global_load_dwordx4 v[86:89], v[70:71], off nt
	global_load_dwordx4 v[66:69], v[70:71], off offset:528 nt
	s_nop 0
	global_load_dwordx4 v[70:73], v[70:71], off offset:512 nt
	s_mov_b64 s[0:1], -1
	s_waitcnt vmcnt(15)
	v_pk_add_f32 v[60:61], v[60:61], v[100:101]
	s_waitcnt vmcnt(14)
	v_pk_add_f32 v[62:63], v[62:63], v[102:103]
	v_lshl_add_u64 v[102:103], s[10:11], 0, v[134:135]
	v_lshl_add_u64 v[102:103], v[102:103], 0, v[152:153]
	s_waitcnt vmcnt(12)
	v_pk_add_f32 v[52:53], v[52:53], v[112:113]
	v_pk_add_f32 v[50:51], v[50:51], v[110:111]
	global_store_dwordx4 v[102:103], v[50:53], off offset:512
	s_waitcnt vmcnt(9)
	v_pk_add_f32 v[36:37], v[36:37], v[128:129]
	v_pk_add_f32 v[34:35], v[34:35], v[126:127]
	v_lshl_add_u64 v[50:51], s[10:11], 0, v[136:137]
	v_lshl_add_u64 v[50:51], v[50:51], 0, v[152:153]
	global_store_dwordx4 v[50:51], v[34:37], off offset:512
	s_waitcnt vmcnt(6)
	v_pk_add_f32 v[20:21], v[20:21], v[92:93]
	v_pk_add_f32 v[18:19], v[18:19], v[90:91]
	v_lshl_add_u64 v[34:35], s[10:11], 0, v[96:97]
	v_lshl_add_u64 v[34:35], v[34:35], 0, v[152:153]
	v_pk_add_f32 v[48:49], v[48:49], v[108:109]
	v_pk_add_f32 v[46:47], v[46:47], v[106:107]
	v_pk_add_f32 v[32:33], v[32:33], v[124:125]
	v_pk_add_f32 v[30:31], v[30:31], v[122:123]
	global_store_dwordx4 v[34:35], v[18:21], off offset:512
	v_pk_add_f32 v[16:17], v[16:17], v[80:81]
	v_pk_add_f32 v[14:15], v[14:15], v[78:79]
	v_lshl_add_u64 v[18:19], s[10:11], 0, v[94:95]
	v_pk_add_f32 v[64:65], v[64:65], v[104:105]
	v_pk_add_f32 v[58:59], v[58:59], v[98:99]
	global_store_dwordx4 v[102:103], v[46:49], off offset:528
	v_pk_add_f32 v[44:45], v[44:45], v[116:117]
	v_pk_add_f32 v[42:43], v[42:43], v[114:115]
	v_pk_add_f32 v[48:49], v[56:57], v[120:121]
	v_pk_add_f32 v[46:47], v[54:55], v[118:119]
	global_store_dwordx4 v[50:51], v[30:33], off offset:528
	v_pk_add_f32 v[28:29], v[28:29], v[84:85]
	v_pk_add_f32 v[26:27], v[26:27], v[82:83]
	v_pk_add_f32 v[32:33], v[40:41], v[132:133]
	v_pk_add_f32 v[30:31], v[38:39], v[130:131]
	global_store_dwordx4 v[34:35], v[14:17], off offset:528
	v_lshl_add_u64 v[18:19], v[18:19], 0, v[152:153]
	s_waitcnt vmcnt(9)
	v_pk_add_f32 v[12:13], v[12:13], v[76:77]
	s_waitcnt vmcnt(8)
	v_pk_add_f32 v[16:17], v[24:25], v[88:89]
	v_pk_add_f32 v[14:15], v[22:23], v[86:87]
	v_pk_add_f32 v[10:11], v[10:11], v[74:75]
	s_waitcnt vmcnt(6)
	v_pk_add_f32 v[8:9], v[8:9], v[72:73]
	v_pk_add_f32 v[6:7], v[6:7], v[70:71]
	v_pk_add_f32 v[4:5], v[4:5], v[68:69]
	v_pk_add_f32 v[2:3], v[2:3], v[66:67]
	global_store_dwordx4 v[102:103], v[62:65], off
	global_store_dwordx4 v[102:103], v[58:61], off offset:16
	global_store_dwordx4 v[50:51], v[46:49], off
	global_store_dwordx4 v[50:51], v[42:45], off offset:16
	global_store_dwordx4 v[34:35], v[30:33], off
	global_store_dwordx4 v[34:35], v[26:29], off offset:16
	global_store_dwordx4 v[18:19], v[14:17], off
	global_store_dwordx4 v[18:19], v[10:13], off offset:16
	global_store_dwordx4 v[18:19], v[6:9], off offset:512
	global_store_dwordx4 v[18:19], v[2:5], off offset:528
	s_cbranch_vccnz .LBB0_572
	s_andn2_b64 vcc, exec, s[14:15]
	s_cbranch_vccnz .LBB0_571
	s_barrier
	s_branch .LBB0_571
